# GEMM no-gate epilogue rewritten lean (no gate mul/select, scalar row stepping, no vmcnt(0) drain) plus first two K-loop waits after an epilogue count its 16 stores
# baseline (speedup 1.0000x reference)
; #define PG8_WAIT_V(n) asm volatile("s_waitcnt vmcnt(" #n ")" ::: "memory")
; #define PG8_BAR __builtin_amdgcn_s_barrier()
; template <class Epi, class Sched, bool ALIGN_EPI = false, bool SP2 = false>
; __device__ __forceinline__ void gemm_phase(PG8_LAS unsigned char* lds, const Gemm g, const Sched& S, const Epi& E) {
;     ...
;     for (int i = 0; i < 2; ++i) { int R, C; stage_rc(tid * 16 + i * 8192, R, C); const int Rb = Epi::PERM ? ((R & ~31) + perm32(R & 31)) : R;
;         voffA[i] = (unsigned)(R * K + C) * 2u; voffB[i] = (unsigned)(Rb * K + C) * 2u; }
;     const size_t kstep = (size_t)(BK * 2);
;     const size_t hstep = (size_t)HALF * K * 2;
;     const size_t tstep = 2 * hstep;
;     const unsigned ldsw = (unsigned)wid * 1024u;
;     const int aoff = lds_byte(wr * 64 + fr, fq * 8), boff = lds_byte(wc * 32 + fr, fq * 8);
;     ...
;     Unit cur, nxt; int ui = 0;
;     if (!S.next(0, cur)) return;
;     f32x4 acc[2][2][4][2];
; #pragma unroll
;     for (int a = 0; a < 2; ++a)
; #pragma unroll
;         for (int b = 0; b < 2; ++b)
; #pragma unroll
;             for (int m = 0; m < 4; ++m)
; #pragma unroll
;                 for (int n = 0; n < 2; ++n) acc[a][b][m][n] = (f32x4){0.f, 0.f, 0.f, 0.f};
;     bf16x8 At[4][2], B0[2][2], B1[2][2];
;     const char* cA = (const char*)g.A + (size_t)cur.pm * tstep; const char* cB = (const char*)g.Bt + (size_t)cur.pn * tstep;
;     S.a_ready(cur);
;     if constexpr (SP2) {
;         PG8_STAGE(PG8_SB(0, 0), cB, voffB); PG8_STAGE(PG8_SB(0, 1), cB + hstep, voffB); PG8_STAGE(PG8_SA(0, 0), cA, voffA); PG8_STAGE(PG8_SA(0, 1), cA + hstep, voffA);
;         if (wr == 1) PG8_BAR;
;         PG8_WAIT_V(2); PG8_BAR;
;         PG8_STAGE(PG8_SB(1, 0), cB + kstep, voffB); PG8_STAGE(PG8_SA(1, 0), cA + kstep, voffA); PG8_STAGE(PG8_SB(1, 1), cB + hstep + kstep, voffB);
;         PG8_WAIT_V(6); PG8_BAR;
;     } else {
;         PG8_STAGE(PG8_SB(0, 0), cB, voffB); PG8_STAGE(PG8_SA(0, 0), cA, voffA); PG8_STAGE(PG8_SB(0, 1), cB + hstep, voffB); PG8_STAGE(PG8_SA(0, 1), cA + hstep, voffA);
;         if (wr == 1) PG8_BAR;
;         PG8_WAIT_V(4); PG8_BAR;
;         PG8_STAGE(PG8_SB(1, 0), cB + kstep, voffB); PG8_STAGE(PG8_SA(1, 0), cA + kstep, voffA); PG8_STAGE(PG8_SB(1, 1), cB + hstep + kstep, voffB);
;         PG8_WAIT_V(6); PG8_BAR;
.LBB0_404:
	s_mov_b32 s101, 0
	s_add_i32 m0, s61, 0x18000
	v_lshl_add_u64 v[10:11], v[10:11], 0, s[24:25]
	s_waitcnt vmcnt(2)
	s_barrier
	global_load_lds_dwordx4 v[10:11], off
	v_lshl_add_u64 v[6:7], v[6:7], 0, s[24:25]
	s_add_i32 m0, s61, 0x1a000
	s_add_i32 s80, s61, 0x8000
	global_load_lds_dwordx4 v[6:7], off
	v_lshl_add_u64 v[6:7], v[8:9], 0, s[24:25]
	s_mov_b32 m0, s80
	s_add_i32 s81, s61, 0xa000
	global_load_lds_dwordx4 v[6:7], off
	v_lshl_add_u64 v[6:7], v[12:13], 0, s[24:25]
	s_mov_b32 m0, s81
	v_lshl_add_u64 v[4:5], v[4:5], 0, s[24:25]
	global_load_lds_dwordx4 v[6:7], off
	s_add_i32 m0, s61, 0x1c000
	v_lshl_add_u64 v[2:3], v[2:3], 0, s[24:25]
	global_load_lds_dwordx4 v[4:5], off
	s_add_i32 m0, s61, 0x1e000
	s_lshl_b32 s19, s19, 5
	global_load_lds_dwordx4 v[2:3], off
	v_lshrrev_b32_e32 v3, 1, v14
	v_and_b32_e32 v3, 24, v3
	v_and_b32_e32 v2, 15, v14
	v_lshlrev_b32_e32 v4, 1, v3
	v_lshl_or_b32 v160, s31, 6, v2
	v_lshl_or_b32 v2, v2, 6, v4
	v_lshlrev_b32_e32 v4, 2, v14
	s_lshl_b32 s31, s31, 13
	v_and_b32_e32 v4, 32, v4
	v_bitop3_b32 v5, v2, s31, v4 bitop3:0xde
	s_and_b32 s31, s19, 0x60
	s_lshl_b32 s19, s31, 7
	v_bitop3_b32 v161, v2, s19, v4 bitop3:0xde
	v_cvt_f32_ubyte0_e32 v2, s54
	v_rcp_iflag_f32_e32 v2, v2
	s_lshr_b32 s82, s82, 6
	s_add_i32 s83, s82, -2
	s_cmpk_lt_u32 s30, 0x100
	v_mul_f32_e32 v2, 0x4f7ffffe, v2
	v_cvt_u32_f32_e32 v2, v2
	s_cselect_b64 s[34:35], -1, 0
	v_or_b32_e32 v162, s31, v3
	s_sub_i32 s30, 0, s54
	v_readfirstlane_b32 s31, v2
	s_waitcnt vmcnt(6)
	s_mul_i32 s30, s30, s31
	s_mul_hi_u32 s30, s31, s30
	s_mov_b32 s19, s11
	s_mov_b32 s84, 0
	s_add_i32 s85, s31, s30
	v_lshl_add_u64 v[152:153], s[10:11], 0, v[146:147]
	v_lshl_add_u64 v[154:155], s[10:11], 0, v[148:149]
	v_add_u32_e32 v163, 0, v5
	s_barrier
	s_branch .LBB0_407

; #define PG8_STAGE(bufoff, gbase, voff) do { _Pragma("unroll") for (int _i = 0; _i < 2; ++_i) \
;         __builtin_amdgcn_global_load_lds((const unsigned*)((const char*)(gbase) + (voff)[_i]), (PG8_LAS unsigned*)(lds + (bufoff) + ldsw + _i * 8192), 16, 0, 0); } while (0)
; #define PG8_LDA(dst, b, h) do { _Pragma("unroll") for (int m = 0; m < 4; ++m) _Pragma("unroll") for (int k = 0; k < 2; ++k) dst[m][k] = *(const PG8_LAS bf16x8*)(lds + PG8_SA(b, h) + aoff + m * 2048 + k * 1024); } while (0)
; #define PG8_LDB(dst, b, h) do { _Pragma("unroll") for (int n = 0; n < 2; ++n) _Pragma("unroll") for (int k = 0; k < 2; ++k) dst[n][k] = *(const PG8_LAS bf16x8*)(lds + PG8_SB(b, h) + boff + n * 2048 + k * 1024); } while (0)
; #define PG8_MMA(ai, bj, At, Bt) do { __builtin_amdgcn_s_setprio(1); _Pragma("unroll") for (int m = 0; m < 4; ++m) _Pragma("unroll") for (int n = 0; n < 2; ++n) _Pragma("unroll") for (int k = 0; k < 2; ++k) \
;         acc[ai][bj][m][n] = __builtin_amdgcn_mfma_f32_16x16x32_bf16(Bt[n][k], At[m][k], acc[ai][bj][m][n], 0, 0, 0); __builtin_amdgcn_s_setprio(0); } while (0)
; #define PG8_WAIT_V(n) asm volatile("s_waitcnt vmcnt(" #n ")" ::: "memory")
; #define PG8_WAIT_L(n) asm volatile("s_waitcnt lgkmcnt(" #n ")" ::: "memory")
; #define PG8_BAR __builtin_amdgcn_s_barrier()
; #define PG8_SCHED __builtin_amdgcn_sched_barrier(0)
; template <class Epi, class Sched, bool ALIGN_EPI = false, bool SP2 = false>
; __device__ __forceinline__ void gemm_phase(PG8_LAS unsigned char* lds, const Gemm g, const Sched& S, const Epi& E) {
;     ...
;             PG8_LDB(B0, 0, 0); PG8_LDB(B1, 0, 1); PG8_SCHED; PG8_LDA(At, 0, 0); PG8_STAGE(PG8_SA(1, 1), a1 + hstep, voffA);
;             PG8_WAIT_V(8); PG8_WAIT_L(0); PG8_BAR; PG8_MMA(0, 0, At, B0); PG8_MMA(0, 1, At, B1); PG8_BAR; PG8_SCHED;
;             PG8_LDA(At, 0, 1); PG8_STAGE(PG8_SB(0, 0), b2, voffB); PG8_STAGE(PG8_SB(0, 1), b2 + hstep, voffB); PG8_STAGE(PG8_SA(0, 0), a2, voffA);
;             PG8_WAIT_V(8); PG8_WAIT_L(0); PG8_BAR; PG8_MMA(1, 0, At, B0); PG8_MMA(1, 1, At, B1); PG8_BAR; PG8_SCHED;
.LBB0_410:
	s_add_i32 vcc_hi, s28, 2
	s_add_u32 s86, s14, 0x80
	s_addc_u32 s29, s15, 0
	s_add_i32 s88, 0, 0x10000
	s_cmp_eq_u32 s83, s28
	s_cselect_b32 s29, s30, s29
	s_cselect_b32 s28, s31, s86
	s_cselect_b32 s87, s37, vcc_lo
	s_cselect_b32 s86, s45, s47
	s_add_i32 s89, 0, 0x14000
	v_add_u32_e32 v86, s88, v161
	v_add_u32_e32 v172, s89, v161
	ds_read_b128 v[74:77], v86
	ds_read_b128 v[78:81], v86 offset:1024
	ds_read_b128 v[82:85], v86 offset:2048
	ds_read_b128 v[86:89], v86 offset:3072
	ds_read_b128 v[156:159], v172
	ds_read_b128 v[164:167], v172 offset:1024
	ds_read_b128 v[168:171], v172 offset:2048
	ds_read_b128 v[172:175], v172 offset:3072
	v_lshl_add_u64 v[204:205], s[14:15], 0, v[152:153]
	s_add_i32 m0, s61, 0xc000
	ds_read_b128 v[176:179], v163
	ds_read_b128 v[180:183], v163 offset:1024
	ds_read_b128 v[184:187], v163 offset:2048
	ds_read_b128 v[188:191], v163 offset:3072
	ds_read_b128 v[192:195], v163 offset:4096
	ds_read_b128 v[196:199], v163 offset:5120
	ds_read_b128 v[200:203], v163 offset:6144
	ds_read_b128 v[210:213], v163 offset:7168
	global_load_lds_dwordx4 v[204:205], off
	v_lshl_add_u64 v[204:205], s[14:15], 0, v[154:155]
	s_add_i32 m0, s61, 0xe000
	s_nop 0
	global_load_lds_dwordx4 v[204:205], off
	s_cmp_eq_u32 s101, 0
	s_cbranch_scc0 .Lgw1_relaxed
	s_waitcnt vmcnt(8)
	s_branch .Lgw1_done
.Lgw1_relaxed:
	s_waitcnt vmcnt(24)
.Lgw1_done:
	s_waitcnt lgkmcnt(0)
	s_barrier
	s_setprio 1
	s_waitcnt lgkmcnt(0)
	v_mfma_f32_16x16x32_bf16 v[142:145], v[74:77], v[176:179], v[142:145]
	v_mfma_f32_16x16x32_bf16 v[138:141], v[82:85], v[176:179], v[138:141]
	v_mfma_f32_16x16x32_bf16 v[126:129], v[74:77], v[184:187], v[126:129]
	v_mfma_f32_16x16x32_bf16 v[122:125], v[82:85], v[184:187], v[122:125]
	v_mfma_f32_16x16x32_bf16 v[110:113], v[74:77], v[192:195], v[110:113]
	v_mfma_f32_16x16x32_bf16 v[106:109], v[82:85], v[192:195], v[106:109]
	v_mfma_f32_16x16x32_bf16 v[94:97], v[74:77], v[200:203], v[94:97]
	v_mfma_f32_16x16x32_bf16 v[90:93], v[82:85], v[200:203], v[90:93]
	v_mfma_f32_16x16x32_bf16 v[142:145], v[78:81], v[180:183], v[142:145]
	v_mfma_f32_16x16x32_bf16 v[138:141], v[86:89], v[180:183], v[138:141]
	v_mfma_f32_16x16x32_bf16 v[126:129], v[78:81], v[188:191], v[126:129]
	v_mfma_f32_16x16x32_bf16 v[122:125], v[86:89], v[188:191], v[122:125]
	v_mfma_f32_16x16x32_bf16 v[110:113], v[78:81], v[196:199], v[110:113]
	v_mfma_f32_16x16x32_bf16 v[106:109], v[86:89], v[196:199], v[106:109]
	v_mfma_f32_16x16x32_bf16 v[94:97], v[78:81], v[210:213], v[94:97]
	v_mfma_f32_16x16x32_bf16 v[90:93], v[86:89], v[210:213], v[90:93]
	s_setprio 0
	s_setprio 1
	v_mfma_f32_16x16x32_bf16 v[134:137], v[156:159], v[176:179], v[134:137]
	v_mfma_f32_16x16x32_bf16 v[130:133], v[168:171], v[176:179], v[130:133]
	v_mfma_f32_16x16x32_bf16 v[118:121], v[156:159], v[184:187], v[118:121]
	v_mfma_f32_16x16x32_bf16 v[114:117], v[168:171], v[184:187], v[114:117]
	v_mfma_f32_16x16x32_bf16 v[102:105], v[156:159], v[192:195], v[102:105]
	v_mfma_f32_16x16x32_bf16 v[98:101], v[168:171], v[192:195], v[98:101]
	v_mfma_f32_16x16x32_bf16 v[70:73], v[156:159], v[200:203], v[70:73]
	v_mfma_f32_16x16x32_bf16 v[66:69], v[168:171], v[200:203], v[66:69]
	v_mfma_f32_16x16x32_bf16 v[134:137], v[164:167], v[180:183], v[134:137]
	v_mfma_f32_16x16x32_bf16 v[130:133], v[172:175], v[180:183], v[130:133]
	v_mfma_f32_16x16x32_bf16 v[118:121], v[164:167], v[188:191], v[118:121]
	v_mfma_f32_16x16x32_bf16 v[114:117], v[172:175], v[188:191], v[114:117]
	v_mfma_f32_16x16x32_bf16 v[102:105], v[164:167], v[196:199], v[102:105]
	v_mfma_f32_16x16x32_bf16 v[98:101], v[172:175], v[196:199], v[98:101]
	v_mfma_f32_16x16x32_bf16 v[70:73], v[164:167], v[210:213], v[70:73]
	v_mfma_f32_16x16x32_bf16 v[66:69], v[172:175], v[210:213], v[66:69]
	s_setprio 0
	s_barrier
	s_add_i32 s88, s88, s62
	v_lshl_add_u64 v[204:205], s[86:87], 0, v[0:1]
	s_mov_b32 m0, s88
	ds_read_b128 v[176:179], v163 offset:16384
	ds_read_b128 v[180:183], v163 offset:17408
	ds_read_b128 v[184:187], v163 offset:18432
	ds_read_b128 v[188:191], v163 offset:19456
	ds_read_b128 v[192:195], v163 offset:20480
	ds_read_b128 v[196:199], v163 offset:21504
	ds_read_b128 v[200:203], v163 offset:22528
	ds_read_b128 v[210:213], v163 offset:23552
	global_load_lds_dwordx4 v[204:205], off
	s_add_i32 m0, s88, 0x2000
	v_lshl_add_u64 v[226:227], s[86:87], 0, v[150:151]
	s_add_u32 s86, s86, s10
	s_addc_u32 s87, s87, 0
	s_add_i32 s88, s89, s62
	global_load_lds_dwordx4 v[226:227], off
	v_lshl_add_u64 v[228:229], s[86:87], 0, v[0:1]
	s_mov_b32 m0, s88
	v_lshl_add_u64 v[230:231], s[86:87], 0, v[150:151]
	global_load_lds_dwordx4 v[228:229], off
	s_add_i32 m0, s88, 0x2000
	v_lshl_add_u64 v[232:233], s[28:29], 0, v[146:147]
	global_load_lds_dwordx4 v[230:231], off
	s_mov_b32 m0, s61
	v_lshl_add_u64 v[234:235], s[28:29], 0, v[148:149]
	global_load_lds_dwordx4 v[232:233], off
	s_mov_b32 m0, s77
	s_nop 0
	global_load_lds_dwordx4 v[234:235], off
	s_cmp_eq_u32 s101, 0
	s_cbranch_scc0 .Lgw2_relaxed
	s_waitcnt vmcnt(8)
	s_branch .Lgw2_done

; #define PG8_STAGE(bufoff, gbase, voff) do { _Pragma("unroll") for (int _i = 0; _i < 2; ++_i) \
;         __builtin_amdgcn_global_load_lds((const unsigned*)((const char*)(gbase) + (voff)[_i]), (PG8_LAS unsigned*)(lds + (bufoff) + ldsw + _i * 8192), 16, 0, 0); } while (0)
; #define PG8_LDA(dst, b, h) do { _Pragma("unroll") for (int m = 0; m < 4; ++m) _Pragma("unroll") for (int k = 0; k < 2; ++k) dst[m][k] = *(const PG8_LAS bf16x8*)(lds + PG8_SA(b, h) + aoff + m * 2048 + k * 1024); } while (0)
; #define PG8_LDB(dst, b, h) do { _Pragma("unroll") for (int n = 0; n < 2; ++n) _Pragma("unroll") for (int k = 0; k < 2; ++k) dst[n][k] = *(const PG8_LAS bf16x8*)(lds + PG8_SB(b, h) + boff + n * 2048 + k * 1024); } while (0)
; #define PG8_MMA(ai, bj, At, Bt) do { __builtin_amdgcn_s_setprio(1); _Pragma("unroll") for (int m = 0; m < 4; ++m) _Pragma("unroll") for (int n = 0; n < 2; ++n) _Pragma("unroll") for (int k = 0; k < 2; ++k) \
;         acc[ai][bj][m][n] = __builtin_amdgcn_mfma_f32_16x16x32_bf16(Bt[n][k], At[m][k], acc[ai][bj][m][n], 0, 0, 0); __builtin_amdgcn_s_setprio(0); } while (0)
; #define PG8_WAIT_V(n) asm volatile("s_waitcnt vmcnt(" #n ")" ::: "memory")
; #define PG8_WAIT_L(n) asm volatile("s_waitcnt lgkmcnt(" #n ")" ::: "memory")
; #define PG8_BAR __builtin_amdgcn_s_barrier()
; #define PG8_SCHED __builtin_amdgcn_sched_barrier(0)
; template <class Epi, class Sched, bool ALIGN_EPI = false, bool SP2 = false>
; __device__ __forceinline__ void gemm_phase(PG8_LAS unsigned char* lds, const Gemm g, const Sched& S, const Epi& E) {
;     ...
;             PG8_WAIT_V(8); PG8_WAIT_L(0); PG8_BAR; PG8_MMA(1, 0, At, B0); PG8_MMA(1, 1, At, B1); PG8_BAR; PG8_SCHED;
;             PG8_LDB(B0, 1, 0); PG8_LDB(B1, 1, 1); PG8_SCHED; PG8_LDA(At, 1, 0); PG8_STAGE(PG8_SA(0, 1), a2 + hstep, voffA);
;             PG8_WAIT_V(8); PG8_WAIT_L(0); PG8_BAR; PG8_MMA(0, 0, At, B0); PG8_MMA(0, 1, At, B1); PG8_BAR; PG8_SCHED;
.Lgw2_done:
	s_mov_b32 s101, 0
	s_waitcnt lgkmcnt(0)
	s_barrier
	s_setprio 1
	s_waitcnt lgkmcnt(0)
	v_mfma_f32_16x16x32_bf16 v[62:65], v[74:77], v[176:179], v[62:65]
	v_mfma_f32_16x16x32_bf16 v[58:61], v[82:85], v[176:179], v[58:61]
	v_mfma_f32_16x16x32_bf16 v[46:49], v[74:77], v[184:187], v[46:49]
	v_mfma_f32_16x16x32_bf16 v[42:45], v[82:85], v[184:187], v[42:45]
	v_mfma_f32_16x16x32_bf16 v[30:33], v[74:77], v[192:195], v[30:33]
	v_mfma_f32_16x16x32_bf16 v[26:29], v[82:85], v[192:195], v[26:29]
	v_mfma_f32_16x16x32_bf16 v[14:17], v[74:77], v[200:203], v[14:17]
	v_mfma_f32_16x16x32_bf16 v[10:13], v[82:85], v[200:203], v[10:13]
	v_mfma_f32_16x16x32_bf16 v[62:65], v[78:81], v[180:183], v[62:65]
	v_mfma_f32_16x16x32_bf16 v[58:61], v[86:89], v[180:183], v[58:61]
	v_mfma_f32_16x16x32_bf16 v[46:49], v[78:81], v[188:191], v[46:49]
	v_mfma_f32_16x16x32_bf16 v[42:45], v[86:89], v[188:191], v[42:45]
	v_mfma_f32_16x16x32_bf16 v[30:33], v[78:81], v[196:199], v[30:33]
	v_mfma_f32_16x16x32_bf16 v[26:29], v[86:89], v[196:199], v[26:29]
	v_mfma_f32_16x16x32_bf16 v[14:17], v[78:81], v[210:213], v[14:17]
	v_mfma_f32_16x16x32_bf16 v[10:13], v[86:89], v[210:213], v[10:13]
	s_setprio 0
	s_setprio 1
	v_mfma_f32_16x16x32_bf16 v[54:57], v[156:159], v[176:179], v[54:57]
	v_mfma_f32_16x16x32_bf16 v[50:53], v[168:171], v[176:179], v[50:53]
	v_mfma_f32_16x16x32_bf16 v[38:41], v[156:159], v[184:187], v[38:41]
	v_mfma_f32_16x16x32_bf16 v[34:37], v[168:171], v[184:187], v[34:37]
	v_mfma_f32_16x16x32_bf16 v[22:25], v[156:159], v[192:195], v[22:25]
	v_mfma_f32_16x16x32_bf16 v[18:21], v[168:171], v[192:195], v[18:21]
	v_mfma_f32_16x16x32_bf16 v[6:9], v[156:159], v[200:203], v[6:9]
	v_mfma_f32_16x16x32_bf16 v[2:5], v[168:171], v[200:203], v[2:5]
	v_mfma_f32_16x16x32_bf16 v[54:57], v[164:167], v[180:183], v[54:57]
	v_mfma_f32_16x16x32_bf16 v[50:53], v[172:175], v[180:183], v[50:53]
	v_mfma_f32_16x16x32_bf16 v[38:41], v[164:167], v[188:191], v[38:41]
	v_mfma_f32_16x16x32_bf16 v[34:37], v[172:175], v[188:191], v[34:37]
	v_mfma_f32_16x16x32_bf16 v[22:25], v[164:167], v[196:199], v[22:25]
	v_mfma_f32_16x16x32_bf16 v[18:21], v[172:175], v[196:199], v[18:21]
	v_mfma_f32_16x16x32_bf16 v[6:9], v[164:167], v[210:213], v[6:9]
	v_mfma_f32_16x16x32_bf16 v[2:5], v[172:175], v[210:213], v[2:5]
	s_setprio 0
	s_barrier
	s_add_i32 s86, 0, 0x18000
	s_add_i32 s87, 0, 0x1c000
	v_add_u32_e32 v86, s86, v161
	v_add_u32_e32 v172, s87, v161
	ds_read_b128 v[74:77], v86
	ds_read_b128 v[78:81], v86 offset:1024
	ds_read_b128 v[82:85], v86 offset:2048
	ds_read_b128 v[86:89], v86 offset:3072
	ds_read_b128 v[156:159], v172
	ds_read_b128 v[164:167], v172 offset:1024
	ds_read_b128 v[168:171], v172 offset:2048
	ds_read_b128 v[172:175], v172 offset:3072
	s_add_u32 s28, s28, s10
	s_addc_u32 s29, s29, 0
	s_mov_b32 m0, s78
	v_lshl_add_u64 v[236:237], s[28:29], 0, v[146:147]
	ds_read_b128 v[176:179], v163 offset:32768
	ds_read_b128 v[180:183], v163 offset:33792
	ds_read_b128 v[184:187], v163 offset:34816
	ds_read_b128 v[188:191], v163 offset:35840
	ds_read_b128 v[192:195], v163 offset:36864
	ds_read_b128 v[196:199], v163 offset:37888
	ds_read_b128 v[200:203], v163 offset:38912
	ds_read_b128 v[210:213], v163 offset:39936
	global_load_lds_dwordx4 v[236:237], off
	v_lshl_add_u64 v[236:237], s[28:29], 0, v[148:149]
	s_mov_b32 m0, s79
	s_nop 0
	global_load_lds_dwordx4 v[236:237], off
	s_waitcnt vmcnt(8)
	s_waitcnt lgkmcnt(0)
	s_barrier
	s_setprio 1
	s_waitcnt lgkmcnt(0)
	v_mfma_f32_16x16x32_bf16 v[142:145], v[74:77], v[176:179], v[142:145]
	v_mfma_f32_16x16x32_bf16 v[138:141], v[82:85], v[176:179], v[138:141]
	v_mfma_f32_16x16x32_bf16 v[126:129], v[74:77], v[184:187], v[126:129]
	v_mfma_f32_16x16x32_bf16 v[122:125], v[82:85], v[184:187], v[122:125]
	v_mfma_f32_16x16x32_bf16 v[110:113], v[74:77], v[192:195], v[110:113]
	v_mfma_f32_16x16x32_bf16 v[106:109], v[82:85], v[192:195], v[106:109]
	v_mfma_f32_16x16x32_bf16 v[94:97], v[74:77], v[200:203], v[94:97]
	v_mfma_f32_16x16x32_bf16 v[90:93], v[82:85], v[200:203], v[90:93]
	v_mfma_f32_16x16x32_bf16 v[142:145], v[78:81], v[180:183], v[142:145]
	v_mfma_f32_16x16x32_bf16 v[138:141], v[86:89], v[180:183], v[138:141]
	v_mfma_f32_16x16x32_bf16 v[126:129], v[78:81], v[188:191], v[126:129]
	v_mfma_f32_16x16x32_bf16 v[122:125], v[86:89], v[188:191], v[122:125]
	v_mfma_f32_16x16x32_bf16 v[110:113], v[78:81], v[196:199], v[110:113]
	v_mfma_f32_16x16x32_bf16 v[106:109], v[86:89], v[196:199], v[106:109]
	v_mfma_f32_16x16x32_bf16 v[94:97], v[78:81], v[210:213], v[94:97]
	v_mfma_f32_16x16x32_bf16 v[90:93], v[86:89], v[210:213], v[90:93]
	s_setprio 0
	s_setprio 1
	v_mfma_f32_16x16x32_bf16 v[134:137], v[156:159], v[176:179], v[134:137]
	v_mfma_f32_16x16x32_bf16 v[130:133], v[168:171], v[176:179], v[130:133]
	v_mfma_f32_16x16x32_bf16 v[118:121], v[156:159], v[184:187], v[118:121]
	v_mfma_f32_16x16x32_bf16 v[114:117], v[168:171], v[184:187], v[114:117]
	v_mfma_f32_16x16x32_bf16 v[102:105], v[156:159], v[192:195], v[102:105]
	v_mfma_f32_16x16x32_bf16 v[98:101], v[168:171], v[192:195], v[98:101]
	v_mfma_f32_16x16x32_bf16 v[70:73], v[156:159], v[200:203], v[70:73]
	v_mfma_f32_16x16x32_bf16 v[66:69], v[168:171], v[200:203], v[66:69]
	v_mfma_f32_16x16x32_bf16 v[134:137], v[164:167], v[180:183], v[134:137]
	v_mfma_f32_16x16x32_bf16 v[130:133], v[172:175], v[180:183], v[130:133]
	v_mfma_f32_16x16x32_bf16 v[118:121], v[164:167], v[188:191], v[118:121]
	v_mfma_f32_16x16x32_bf16 v[114:117], v[172:175], v[188:191], v[114:117]
	v_mfma_f32_16x16x32_bf16 v[102:105], v[164:167], v[196:199], v[102:105]
	v_mfma_f32_16x16x32_bf16 v[98:101], v[172:175], v[196:199], v[98:101]
	v_mfma_f32_16x16x32_bf16 v[70:73], v[164:167], v[210:213], v[70:73]
	v_mfma_f32_16x16x32_bf16 v[66:69], v[172:175], v[210:213], v[66:69]
	s_setprio 0
	s_barrier
; #define PG8_STAGE(bufoff, gbase, voff) do { _Pragma("unroll") for (int _i = 0; _i < 2; ++_i) \
;         __builtin_amdgcn_global_load_lds((const unsigned*)((const char*)(gbase) + (voff)[_i]), (PG8_LAS unsigned*)(lds + (bufoff) + ldsw + _i * 8192), 16, 0, 0); } while (0)
; #define PG8_LDA(dst, b, h) do { _Pragma("unroll") for (int m = 0; m < 4; ++m) _Pragma("unroll") for (int k = 0; k < 2; ++k) dst[m][k] = *(const PG8_LAS bf16x8*)(lds + PG8_SA(b, h) + aoff + m * 2048 + k * 1024); } while (0)
; #define PG8_WAIT_V(n) asm volatile("s_waitcnt vmcnt(" #n ")" ::: "memory")
; template <class Epi, class Sched, bool ALIGN_EPI = false, bool SP2 = false>
; __device__ __forceinline__ void gemm_phase(PG8_LAS unsigned char* lds, const Gemm g, const Sched& S, const Epi& E) {
;     ...
;             PG8_LDA(At, 1, 1); PG8_STAGE(PG8_SB(1, 0), b3, voffB); PG8_STAGE(PG8_SB(1, 1), b3 + hstep, voffB); PG8_STAGE(PG8_SA(1, 0), a3, voffA);
;             PG8_WAIT_V(8); PG8_WAIT_L(0); PG8_BAR; PG8_MMA(1, 0, At, B0); PG8_MMA(1, 1, At, B1); PG8_BAR; PG8_SCHED;
;             } else {
;             PG8_LDB(B0, 0, 0); PG8_SCHED; PG8_LDA(At, 0, 0); PG8_STAGE(PG8_SA(1, 1), a1 + hstep, voffA);
;             PG8_WAIT_L(8); PG8_BAR; PG8_WAIT_L(0); PG8_MMA(0, 0, At, B0); PG8_BAR; PG8_SCHED;
;             PG8_LDB(B1, 0, 1); PG8_STAGE(PG8_SB(0, 0), b2, voffB);
;             PG8_BAR; PG8_WAIT_L(0); PG8_MMA(0, 1, At, B1); PG8_BAR;
;             PG8_LDA(At, 0, 1); PG8_STAGE(PG8_SA(0, 0), a2, voffA);
;             PG8_BAR; PG8_WAIT_L(0); PG8_MMA(1, 0, At, B0); PG8_BAR; PG8_SCHED;
;             PG8_STAGE(PG8_SB(0, 1), b2 + hstep, voffB);
;             PG8_WAIT_V(6); PG8_BAR; PG8_MMA(1, 1, At, B1); PG8_BAR;
;             PG8_LDB(B0, 1, 0); PG8_SCHED; PG8_LDA(At, 1, 0); PG8_STAGE(PG8_SA(0, 1), a2 + hstep, voffA);
;             PG8_WAIT_L(8); PG8_BAR; PG8_WAIT_L(0); PG8_MMA(0, 0, At, B0); PG8_BAR; PG8_SCHED;
;             PG8_LDB(B1, 1, 1); PG8_STAGE(PG8_SB(1, 0), b3, voffB);
;             PG8_BAR; PG8_WAIT_L(0); PG8_MMA(0, 1, At, B1); PG8_BAR;
;             PG8_LDA(At, 1, 1); PG8_STAGE(PG8_SA(1, 0), a3, voffA);
;             PG8_BAR; PG8_WAIT_L(0); PG8_MMA(1, 0, At, B0); PG8_BAR; PG8_SCHED;
;             PG8_STAGE(PG8_SB(1, 1), b3 + hstep, voffB);
;             PG8_WAIT_V(6); PG8_BAR; PG8_MMA(1, 1, At, B1); PG8_BAR;
;             }
;         }
;         if constexpr (ALIGN_EPI) { if (wr == 0) PG8_BAR; }
	s_add_i32 s28, s86, s62
	v_lshl_add_u64 v[204:205], v[204:205], 0, s[24:25]
	s_mov_b32 m0, s28
	ds_read_b128 v[176:179], v163 offset:49152
	ds_read_b128 v[180:183], v163 offset:50176
	ds_read_b128 v[184:187], v163 offset:51200
	ds_read_b128 v[188:191], v163 offset:52224
	ds_read_b128 v[192:195], v163 offset:53248
	ds_read_b128 v[196:199], v163 offset:54272
	ds_read_b128 v[200:203], v163 offset:55296
	ds_read_b128 v[210:213], v163 offset:56320
	global_load_lds_dwordx4 v[204:205], off
	v_lshl_add_u64 v[204:205], v[226:227], 0, s[24:25]
	s_add_i32 m0, s28, 0x2000
	s_add_i32 s28, s87, s62
	global_load_lds_dwordx4 v[204:205], off
	v_lshl_add_u64 v[204:205], v[228:229], 0, s[24:25]
	s_mov_b32 m0, s28
	s_nop 0
	global_load_lds_dwordx4 v[204:205], off
	v_lshl_add_u64 v[204:205], v[230:231], 0, s[24:25]
	s_add_i32 m0, s28, 0x2000
	s_nop 0
	global_load_lds_dwordx4 v[204:205], off
	v_lshl_add_u64 v[204:205], v[232:233], 0, s[24:25]
	s_mov_b32 m0, s80
	s_nop 0
	global_load_lds_dwordx4 v[204:205], off
	v_lshl_add_u64 v[204:205], v[234:235], 0, s[24:25]
	s_mov_b32 m0, s81
	s_nop 0
	global_load_lds_dwordx4 v[204:205], off
	s_waitcnt vmcnt(8)
	s_waitcnt lgkmcnt(0)
	s_barrier
	s_setprio 1
	s_waitcnt lgkmcnt(0)
	v_mfma_f32_16x16x32_bf16 v[62:65], v[74:77], v[176:179], v[62:65]
	v_mfma_f32_16x16x32_bf16 v[58:61], v[82:85], v[176:179], v[58:61]
	v_mfma_f32_16x16x32_bf16 v[46:49], v[74:77], v[184:187], v[46:49]
	v_mfma_f32_16x16x32_bf16 v[42:45], v[82:85], v[184:187], v[42:45]
	v_mfma_f32_16x16x32_bf16 v[30:33], v[74:77], v[192:195], v[30:33]
	v_mfma_f32_16x16x32_bf16 v[26:29], v[82:85], v[192:195], v[26:29]
	v_mfma_f32_16x16x32_bf16 v[14:17], v[74:77], v[200:203], v[14:17]
	v_mfma_f32_16x16x32_bf16 v[10:13], v[82:85], v[200:203], v[10:13]
	v_mfma_f32_16x16x32_bf16 v[62:65], v[78:81], v[180:183], v[62:65]
	v_mfma_f32_16x16x32_bf16 v[58:61], v[86:89], v[180:183], v[58:61]
	v_mfma_f32_16x16x32_bf16 v[46:49], v[78:81], v[188:191], v[46:49]
	v_mfma_f32_16x16x32_bf16 v[42:45], v[86:89], v[188:191], v[42:45]
	v_mfma_f32_16x16x32_bf16 v[30:33], v[78:81], v[196:199], v[30:33]
	v_mfma_f32_16x16x32_bf16 v[26:29], v[86:89], v[196:199], v[26:29]
	v_mfma_f32_16x16x32_bf16 v[14:17], v[78:81], v[210:213], v[14:17]
	v_mfma_f32_16x16x32_bf16 v[10:13], v[86:89], v[210:213], v[10:13]
	s_setprio 0
	s_setprio 1
	v_mfma_f32_16x16x32_bf16 v[54:57], v[156:159], v[176:179], v[54:57]
	v_mfma_f32_16x16x32_bf16 v[50:53], v[168:171], v[176:179], v[50:53]
	v_mfma_f32_16x16x32_bf16 v[38:41], v[156:159], v[184:187], v[38:41]
	v_mfma_f32_16x16x32_bf16 v[34:37], v[168:171], v[184:187], v[34:37]
	v_mfma_f32_16x16x32_bf16 v[22:25], v[156:159], v[192:195], v[22:25]
	v_mfma_f32_16x16x32_bf16 v[18:21], v[168:171], v[192:195], v[18:21]
	v_mfma_f32_16x16x32_bf16 v[6:9], v[156:159], v[200:203], v[6:9]
	v_mfma_f32_16x16x32_bf16 v[2:5], v[168:171], v[200:203], v[2:5]
	v_mfma_f32_16x16x32_bf16 v[54:57], v[164:167], v[180:183], v[54:57]
	v_mfma_f32_16x16x32_bf16 v[50:53], v[172:175], v[180:183], v[50:53]
	v_mfma_f32_16x16x32_bf16 v[38:41], v[164:167], v[188:191], v[38:41]
	v_mfma_f32_16x16x32_bf16 v[34:37], v[172:175], v[188:191], v[34:37]
	v_mfma_f32_16x16x32_bf16 v[22:25], v[164:167], v[196:199], v[22:25]
	v_mfma_f32_16x16x32_bf16 v[18:21], v[172:175], v[196:199], v[18:21]
	v_mfma_f32_16x16x32_bf16 v[6:9], v[164:167], v[210:213], v[6:9]
	v_mfma_f32_16x16x32_bf16 v[2:5], v[172:175], v[210:213], v[2:5]
	s_setprio 0
	s_barrier
	s_add_u32 s14, s14, 0x100
	s_addc_u32 s15, s15, 0
	s_add_u32 s47, s47, 0x100
	s_addc_u32 vcc_lo, vcc_lo, 0
	s_cmp_ge_u32 vcc_hi, s82
	s_mov_b32 s28, vcc_hi
	s_cbranch_scc0 .LBB0_410
	s_and_b64 vcc, exec, s[34:35]
	s_cbranch_vccz .LBB0_413
	s_barrier

; template <class Epi, class Sched, bool ALIGN_EPI = false, bool SP2 = false>
; __device__ __forceinline__ void gemm_phase(PG8_LAS unsigned char* lds, const Gemm g, const Sched& S, const Epi& E) {
;     ...
;         if constexpr (!Epi::AFTER_DRAIN) { E(acc, cur, wr, wc, fr, fq); S.done(cur); }
;         if (!has_next) break;
.Lepi_join:
	s_mov_b32 s101, 1
	s_cbranch_vccnz .LBB0_406
	s_andn2_b64 vcc, exec, s[22:23]
	s_cbranch_vccnz .LBB0_405
	s_barrier
	s_branch .LBB0_405
